# v15 + s_setprio 1 around each MFMA cluster of the attention tile loop (QK halves, PV halves), 0 during softmax VALU
# speedup vs baseline: 1.0133x; 1.0068x over previous
; DI f32x16 mfma32(bf16x8 a, bf16x8 b, f32x16 c) { return __builtin_amdgcn_mfma_f32_32x32x16_bf16(a, b, c, 0, 0, 0); }
; DI void attn_phase(const Params& p, unsigned char* smem) {
;     ...
;         auto qk_half = [&](const bf16_t* kb, int kh, int ksw) __attribute__((always_inline)) {
;             f32x16 S = NEGM;
; #pragma unroll
;             for (int ks = 0; ks < 4; ++ks)
;                 S = mfma32(*(const bf16x8*)(kb + (kh * 32 + l31) * 128 + (((comp * 8 + ks * 2 + hi) ^ ksw) * 8)), Qf[ks], S);
;             return S;
;         };
;         auto softmax_half = [&](f32x16& S, f32x16* Spend, int j, int kh, int kbase, bool need_mask, bf16x8 (&P)[2]) __attribute__((always_inline)) {
;             if (need_mask) {
; #pragma unroll
;                 for (int i = 0; i < 16; ++i) {
;                     const int key = kh * 32 + 8 * (i >> 2) + 4 * hi + (i & 3);
;                     const bool vis = (j == 0) ? (key < 16) : (kbase + key <= q0 + l31);
;                     if (!vis) S[i] = -INFINITY;
;                 }
;     ...
;                 const bf16_t* kb = sK + buf * 64 * 128;
;                 const bf16_t* vb = sV + buf * 128 * 64;
;                 const bool need_mask = (j == 0) || (kbase + 63 > q0);
;                 const bool act1 = (j >= 1) && (kbase + 32 <= q0 + 31);
;                 const int ksw = l31 & 15, dsw = (l31 >> 1) & 7;
;                 f32x16 S0 = qk_half(kb, 0, ksw);
;                 bf16x8 P[2];
;                 if (act1) {
;                     f32x16 S1 = qk_half(kb, 1, ksw);
.LBB0_1277:
	s_sub_i32 s19, s47, 32
	s_cmp_eq_u32 s18, 0
	s_cselect_b64 s[20:21], -1, 0
	v_cmp_le_i32_e32 vcc, s19, v196
	s_or_b64 s[24:25], s[20:21], vcc
	s_and_saveexec_b64 s[18:19], s[24:25]
	s_cbranch_execz .LBB0_1301
	s_mov_b32 s22, s100
	v_add_u32_e32 v12, s22, v192
	v_lshl_add_u32 v1, v182, 1, v12
	v_lshl_add_u32 v3, v183, 1, v12
	v_lshl_add_u32 v204, v184, 1, v12
	v_lshl_add_u32 v205, v185, 1, v12
	ds_read_b128 v[4:7], v1
	ds_read_b128 v[8:11], v3
	ds_read_b128 v[206:209], v204
	ds_read_b128 v[210:213], v205
	ds_read_b128 v[214:217], v1 offset:8192
	ds_read_b128 v[218:221], v3 offset:8192
	ds_read_b128 v[222:225], v204 offset:8192
	ds_read_b128 v[226:229], v205 offset:8192
	s_add_i32 s49, s22, 0
	s_add_i32 s22, s47, 31
	v_cmp_gt_i32_e32 vcc, s22, v195
	s_or_b64 s[22:23], s[20:21], vcc
	s_xor_b64 s[24:25], s[20:21], -1
	v_cmp_le_i32_e32 vcc, s47, v196
	s_setprio 1
	s_waitcnt lgkmcnt(6)
	v_mfma_f32_32x32x16_bf16 v[96:111], v[4:7], v[128:131], v[80:95]
	s_and_b64 s[24:25], s[24:25], vcc
	v_mfma_f32_32x32x16_bf16 v[96:111], v[8:11], v[132:135], v[96:111]
	s_waitcnt lgkmcnt(4)
	v_mfma_f32_32x32x16_bf16 v[96:111], v[206:209], v[136:139], v[96:111]
	v_mfma_f32_32x32x16_bf16 v[96:111], v[210:213], v[140:143], v[96:111]
	s_setprio 0
	s_and_saveexec_b64 s[26:27], s[24:25]
	s_xor_b64 s[24:25], exec, s[26:27]
	s_cbranch_execz .LBB0_1292
	v_mov_b64_e32 v[126:127], v[94:95]
	v_mov_b64_e32 v[124:125], v[92:93]
	v_mov_b64_e32 v[122:123], v[90:91]
	v_mov_b64_e32 v[120:121], v[88:89]
	v_mov_b64_e32 v[118:119], v[86:87]
	v_mov_b64_e32 v[116:117], v[84:85]
	v_mov_b64_e32 v[114:115], v[82:83]
	v_mov_b64_e32 v[112:113], v[80:81]
	s_setprio 1
	s_waitcnt lgkmcnt(2)
	s_nop 0
	v_mfma_f32_32x32x16_bf16 v[112:127], v[214:217], v[128:131], v[112:127]
	v_mfma_f32_32x32x16_bf16 v[112:127], v[218:221], v[132:135], v[112:127]
	s_waitcnt lgkmcnt(0)
	v_mfma_f32_32x32x16_bf16 v[112:127], v[222:225], v[136:139], v[112:127]
	v_mfma_f32_32x32x16_bf16 v[112:127], v[226:229], v[140:143], v[112:127]
	s_setprio 0
	s_and_saveexec_b64 s[26:27], s[22:23]
	s_cbranch_execz .LBB0_1283
	v_add_u32_e32 v1, s47, v152
	v_subrev_u32_e32 v3, 32, v1
	v_cmp_lt_i32_e32 vcc, v3, v197
	s_nop 1
	v_cndmask_b32_e32 v97, v194, v97, vcc
	v_cmp_le_i32_e32 vcc, v3, v197
	v_subrev_u32_e32 v3, 30, v1
	s_nop 0
	v_cndmask_b32_e32 v96, v194, v96, vcc
	v_cmp_le_i32_e32 vcc, v3, v197
	v_subrev_u32_e32 v3, 29, v1
	s_nop 0
	v_cndmask_b32_e32 v98, v194, v98, vcc
	v_cmp_le_i32_e32 vcc, v3, v197
	v_subrev_u32_e32 v3, 24, v1
	s_nop 0
	v_cndmask_b32_e32 v99, v194, v99, vcc
	v_cmp_le_i32_e32 vcc, v3, v197
	v_subrev_u32_e32 v3, 23, v1
	s_nop 0
	v_cndmask_b32_e32 v100, v194, v100, vcc
	v_cmp_le_i32_e32 vcc, v3, v197
	v_subrev_u32_e32 v3, 22, v1
	s_nop 0
	v_cndmask_b32_e32 v101, v194, v101, vcc
	v_cmp_le_i32_e32 vcc, v3, v197
	v_subrev_u32_e32 v3, 21, v1
	s_nop 0
	v_cndmask_b32_e32 v102, v194, v102, vcc
	v_cmp_le_i32_e32 vcc, v3, v197
	v_add_u32_e32 v3, -16, v1
	s_nop 0
	v_cndmask_b32_e32 v103, v194, v103, vcc
	v_cmp_le_i32_e32 vcc, v3, v197
	v_add_u32_e32 v3, -15, v1
	s_nop 0
	v_cndmask_b32_e32 v104, v194, v104, vcc
	v_cmp_le_i32_e32 vcc, v3, v197
	v_add_u32_e32 v3, -14, v1
	s_nop 0
	v_cndmask_b32_e32 v105, v194, v105, vcc
	v_cmp_le_i32_e32 vcc, v3, v197
	v_add_u32_e32 v3, -13, v1
	s_nop 0
	v_cndmask_b32_e32 v106, v194, v106, vcc
	v_cmp_le_i32_e32 vcc, v3, v197
	v_add_u32_e32 v3, -8, v1
	s_nop 0
	v_cndmask_b32_e32 v107, v194, v107, vcc
	v_cmp_le_i32_e32 vcc, v3, v197
	v_add_u32_e32 v3, -7, v1
	s_nop 0
	v_cndmask_b32_e32 v108, v194, v108, vcc
	v_cmp_le_i32_e32 vcc, v3, v197
	v_add_u32_e32 v3, -6, v1
	v_add_u32_e32 v1, -5, v1
	v_cndmask_b32_e32 v109, v194, v109, vcc
	v_cmp_le_i32_e32 vcc, v3, v197
	s_nop 1
	v_cndmask_b32_e32 v110, v194, v110, vcc
	v_cmp_gt_i32_e32 vcc, v1, v197
	s_and_saveexec_b64 s[28:29], vcc
	v_mov_b32_e32 v111, s41
	s_or_b64 exec, exec, s[28:29]

; DI f32x16 mfma32(bf16x8 a, bf16x8 b, f32x16 c) { return __builtin_amdgcn_mfma_f32_32x32x16_bf16(a, b, c, 0, 0, 0); }
; DI void attn_phase(const Params& p, unsigned char* smem) {
;     ...
;             if (need_mask) {
; #pragma unroll
;                 for (int i = 0; i < 16; ++i) {
;                     const int key = kh * 32 + 8 * (i >> 2) + 4 * hi + (i & 3);
;                     const bool vis = (j == 0) ? (key < 16) : (kbase + key <= q0 + l31);
;                     if (!vis) S[i] = -INFINITY;
;                 }
;     ...
;             float ls = 0.f;
; #pragma unroll
;             for (int i = 0; i < 16; ++i) { const float e = __builtin_amdgcn_exp2f(S[i]); S[i] = e; ls += e; }
;             lrun += ls;
;             P[0] = pack8(S, 0); P[1] = pack8(S, 1);
;         };
;         auto pv_half = [&](const bf16_t* vb, int kh, int dsw, const bf16x8 (&P)[2]) __attribute__((always_inline)) {
; #pragma unroll
;             for (int s2 = 0; s2 < 2; ++s2) {
;                 const int u = kh * 2 + s2;
; #pragma unroll
;                 for (int d = 0; d < 4; ++d) {
;                     const bf16x8 A = *(const bf16x8*)(vb + (d * 32 + l31) * 64 + (((2 * u + hi) ^ dsw) * 8));
;                     O[d] = mfma32(A, P[s2], O[d]);
;                 }
;             }
;         };
.LBB0_1285:
	v_lshl_add_u32 v1, v186, 1, s49
	v_exp_f32_e32 v3, v96
	v_lshl_add_u32 v96, v187, 1, v1
	ds_read_b128 v[12:15], v96 offset:32768
	ds_read_b128 v[200:203], v96 offset:36864
	v_exp_f32_e32 v4, v97
	v_exp_f32_e32 v5, v98
	v_exp_f32_e32 v6, v99
	v_exp_f32_e32 v7, v100
	v_exp_f32_e32 v8, v101
	v_exp_f32_e32 v9, v102
	v_exp_f32_e32 v10, v103
	v_cvt_pk_bf16_f32 v98, v3, v4
	v_cvt_pk_bf16_f32 v99, v5, v6
	v_cvt_pk_bf16_f32 v100, v7, v8
	v_cvt_pk_bf16_f32 v101, v9, v10
	v_lshl_add_u32 v199, v188, 1, v1
	v_exp_f32_e32 v11, v104
	s_setprio 1
	s_waitcnt lgkmcnt(0)
	v_mfma_f32_32x32x16_bf16 v[64:79], v[12:15], v[98:101], v[64:79]
	ds_read_b128 v[12:15], v96 offset:40960
	v_exp_f32_e32 v97, v110
	v_mfma_f32_32x32x16_bf16 v[48:63], v[200:203], v[98:101], v[48:63]
	ds_read_b128 v[200:203], v96 offset:45056
	v_exp_f32_e32 v96, v109
	s_waitcnt lgkmcnt(0)
	v_mfma_f32_32x32x16_bf16 v[32:47], v[12:15], v[98:101], v[32:47]
	v_exp_f32_e32 v12, v105
	ds_read_b128 v[102:105], v199 offset:32768
	v_exp_f32_e32 v13, v106
	v_exp_f32_e32 v14, v107
	v_exp_f32_e32 v15, v108
	v_cvt_pk_bf16_f32 v106, v11, v12
	v_cvt_pk_bf16_f32 v107, v13, v14
	v_mfma_f32_32x32x16_bf16 v[16:31], v[200:203], v[98:101], v[16:31]
	ds_read_b128 v[200:203], v199 offset:36864
	v_exp_f32_e32 v98, v111
	v_cvt_pk_bf16_f32 v108, v15, v96
	v_cvt_pk_bf16_f32 v109, v97, v98
	s_waitcnt lgkmcnt(0)
	s_nop 0
	v_mfma_f32_32x32x16_bf16 v[64:79], v[102:105], v[106:109], v[64:79]
	v_mfma_f32_32x32x16_bf16 v[48:63], v[200:203], v[106:109], v[48:63]
	ds_read_b128 v[100:103], v199 offset:40960
	ds_read_b128 v[200:203], v199 offset:45056
	s_waitcnt lgkmcnt(0)
	v_mfma_f32_32x32x16_bf16 v[32:47], v[100:103], v[106:109], v[32:47]
	v_mfma_f32_32x32x16_bf16 v[16:31], v[200:203], v[106:109], v[16:31]
	s_setprio 0
	s_and_saveexec_b64 s[26:27], s[22:23]
	s_cbranch_execz .LBB0_1289
	v_add_u32_e32 v99, s47, v152
	v_cmp_le_i32_e32 vcc, v99, v197
	v_add_u32_e32 v100, 1, v99
	s_nop 0
	v_cndmask_b32_e32 v112, v194, v112, vcc
	v_cmp_le_i32_e32 vcc, v100, v197
	v_add_u32_e32 v100, 2, v99
	s_nop 0
	v_cndmask_b32_e32 v113, v194, v113, vcc
	v_cmp_le_i32_e32 vcc, v100, v197
	v_add_u32_e32 v100, 3, v99
	s_nop 0
	v_cndmask_b32_e32 v114, v194, v114, vcc
	v_cmp_le_i32_e32 vcc, v100, v197
	v_add_u32_e32 v100, 8, v99
	s_nop 0
	v_cndmask_b32_e32 v115, v194, v115, vcc
	v_cmp_le_i32_e32 vcc, v100, v197
	v_add_u32_e32 v100, 9, v99
	s_nop 0
	v_cndmask_b32_e32 v116, v194, v116, vcc
	v_cmp_le_i32_e32 vcc, v100, v197
	v_add_u32_e32 v100, 10, v99
	s_nop 0
	v_cndmask_b32_e32 v117, v194, v117, vcc
	v_cmp_le_i32_e32 vcc, v100, v197
	v_add_u32_e32 v100, 11, v99
	s_nop 0
	v_cndmask_b32_e32 v118, v194, v118, vcc
	v_cmp_le_i32_e32 vcc, v100, v197
	v_add_u32_e32 v100, 16, v99
	s_nop 0
	v_cndmask_b32_e32 v119, v194, v119, vcc
	v_cmp_le_i32_e32 vcc, v100, v197
	v_add_u32_e32 v100, 17, v99
	s_nop 0
	v_cndmask_b32_e32 v120, v194, v120, vcc
	v_cmp_le_i32_e32 vcc, v100, v197
	v_add_u32_e32 v100, 18, v99
	s_nop 0
	v_cndmask_b32_e32 v121, v194, v121, vcc
	v_cmp_le_i32_e32 vcc, v100, v197
	v_add_u32_e32 v100, 19, v99
	s_nop 0
	v_cndmask_b32_e32 v122, v194, v122, vcc
	v_cmp_le_i32_e32 vcc, v100, v197
	v_add_u32_e32 v100, 24, v99
	s_nop 0
	v_cndmask_b32_e32 v123, v194, v123, vcc
	v_cmp_le_i32_e32 vcc, v100, v197
	v_add_u32_e32 v100, 25, v99
	s_nop 0
	v_cndmask_b32_e32 v124, v194, v124, vcc
	v_cmp_le_i32_e32 vcc, v100, v197
	v_add_u32_e32 v100, 26, v99
	v_add_u32_e32 v99, 27, v99
	v_cndmask_b32_e32 v125, v194, v125, vcc
	v_cmp_le_i32_e32 vcc, v100, v197
	s_nop 1
	v_cndmask_b32_e32 v126, v194, v126, vcc
	v_cmp_gt_i32_e32 vcc, v99, v197
	s_and_saveexec_b64 s[28:29], vcc
	v_mov_b32_e32 v127, s41
	s_or_b64 exec, exec, s[28:29]

; DI f32x16 mfma32(bf16x8 a, bf16x8 b, f32x16 c) { return __builtin_amdgcn_mfma_f32_32x32x16_bf16(a, b, c, 0, 0, 0); }
; DI void attn_phase(const Params& p, unsigned char* smem) {
;     ...
;             float ls = 0.f;
; #pragma unroll
;             for (int i = 0; i < 16; ++i) { const float e = __builtin_amdgcn_exp2f(S[i]); S[i] = e; ls += e; }
;             lrun += ls;
;             P[0] = pack8(S, 0); P[1] = pack8(S, 1);
;         };
;         auto pv_half = [&](const bf16_t* vb, int kh, int dsw, const bf16x8 (&P)[2]) __attribute__((always_inline)) {
; #pragma unroll
;             for (int s2 = 0; s2 < 2; ++s2) {
;                 const int u = kh * 2 + s2;
; #pragma unroll
;                 for (int d = 0; d < 4; ++d) {
;                     const bf16x8 A = *(const bf16x8*)(vb + (d * 32 + l31) * 64 + (((2 * u + hi) ^ dsw) * 8));
;                     O[d] = mfma32(A, P[s2], O[d]);
;                 }
;             }
;         };
.LBB0_1291:
	v_lshl_add_u32 v100, v189, 1, v1
	ds_read_b128 v[4:7], v100 offset:32768
	ds_read_b128 v[12:15], v100 offset:36864
	v_exp_f32_e32 v3, v112
	v_exp_f32_e32 v96, v113
	v_exp_f32_e32 v97, v114
	v_exp_f32_e32 v98, v115
	v_exp_f32_e32 v99, v116
	v_exp_f32_e32 v101, v117
	v_exp_f32_e32 v102, v118
	v_exp_f32_e32 v103, v119
	v_cvt_pk_bf16_f32 v8, v3, v96
	v_cvt_pk_bf16_f32 v9, v97, v98
	v_cvt_pk_bf16_f32 v10, v99, v101
	v_cvt_pk_bf16_f32 v11, v102, v103
	v_lshl_add_u32 v1, v190, 1, v1
	v_exp_f32_e32 v104, v120
	s_setprio 1
	s_waitcnt lgkmcnt(0)
	v_mfma_f32_32x32x16_bf16 v[64:79], v[4:7], v[8:11], v[64:79]
	ds_read_b128 v[4:7], v100 offset:40960
	v_exp_f32_e32 v105, v122
	v_exp_f32_e32 v106, v123
	v_exp_f32_e32 v107, v124
	v_exp_f32_e32 v108, v125
	v_exp_f32_e32 v109, v126
	v_exp_f32_e32 v110, v127
	v_mfma_f32_32x32x16_bf16 v[48:63], v[12:15], v[8:11], v[48:63]
	ds_read_b128 v[12:15], v100 offset:45056
	v_exp_f32_e32 v100, v121
	v_add_f32_e32 v3, 0, v3
	v_add_f32_e32 v3, v96, v3
	v_add_f32_e32 v3, v97, v3
	v_add_f32_e32 v3, v98, v3
	v_add_f32_e32 v3, v99, v3
	s_waitcnt lgkmcnt(0)
	v_mfma_f32_32x32x16_bf16 v[32:47], v[4:7], v[8:11], v[32:47]
	ds_read_b128 v[4:7], v1 offset:32768
	v_add_f32_e32 v3, v101, v3
	v_add_f32_e32 v3, v102, v3
	v_add_f32_e32 v3, v103, v3
	v_add_f32_e32 v3, v104, v3
	v_add_f32_e32 v3, v100, v3
	v_mfma_f32_32x32x16_bf16 v[16:31], v[12:15], v[8:11], v[16:31]
	ds_read_b128 v[12:15], v1 offset:36864
	v_cvt_pk_bf16_f32 v8, v104, v100
	v_cvt_pk_bf16_f32 v9, v105, v106
	v_cvt_pk_bf16_f32 v10, v107, v108
	v_cvt_pk_bf16_f32 v11, v109, v110
	s_waitcnt lgkmcnt(0)
	s_nop 0
	v_mfma_f32_32x32x16_bf16 v[64:79], v[4:7], v[8:11], v[64:79]
	ds_read_b128 v[4:7], v1 offset:40960
	v_mfma_f32_32x32x16_bf16 v[48:63], v[12:15], v[8:11], v[48:63]
	ds_read_b128 v[12:15], v1 offset:45056
	v_add_f32_e32 v1, v105, v3
	v_add_f32_e32 v1, v106, v1
	v_add_f32_e32 v1, v107, v1
	v_add_f32_e32 v1, v108, v1
	v_add_f32_e32 v1, v109, v1
	v_add_f32_e32 v1, v110, v1
	s_waitcnt lgkmcnt(0)
	v_mfma_f32_32x32x16_bf16 v[32:47], v[4:7], v[8:11], v[32:47]
	v_add_f32_e32 v2, v2, v1
	v_mfma_f32_32x32x16_bf16 v[16:31], v[12:15], v[8:11], v[16:31]
	s_setprio 0
